# local phase: order of the three heavy unit kinds rotated by workgroup index ((k+w)%3) to de-synchronise unit kinds across workgroups
# speedup vs baseline: 1.0337x; 1.0094x over previous
.LBB0_270:
	s_or_b64 exec, exec, s[0:1]
	v_readlane_b32 s0, v255, 7
	v_readlane_b32 s1, v255, 8
	s_andn2_b64 vcc, exec, s[0:1]
	s_waitcnt lgkmcnt(0)
	s_barrier
	s_cbranch_vccnz .LBB0_521
	v_readlane_b32 s0, v255, 25
	s_lshl_b32 s48, s0, 9
	s_lshl_b32 s8, s0, 4
	s_lshl_b32 s9, s0, 12
	s_lshl_b32 s6, s0, 8
	s_mov_b32 s7, s49
	s_lshl_b32 s10, s0, 10
	s_mov_b32 s11, s49
	s_lshl_b32 s20, s0, 1
	s_lshl_b32 s14, s0, 11
	s_mov_b32 s15, s49
	s_lshl_b32 s21, s0, 3
	s_lshl_b64 s[16:17], s[48:49], 2
	v_readlane_b32 s22, v255, 0
	v_readlane_b32 s1, v255, 26
	s_cmpk_eq_i32 s36, 0x100
	s_cselect_b32 s101, 0, -1
	s_cmp_eq_u32 s101, -1
	s_cbranch_scc1 .Lrot_e
	s_mul_i32 s100, s22, 171
	s_lshr_b32 s100, s100, 9
	s_mul_i32 s100, s100, 3
	s_sub_i32 s100, s22, s100
	s_mul_i32 s100, s100, 0x108
	s_add_i32 s22, s22, s100
.Lrot_e:
	s_branch .LBB0_274
.LBB0_272:
	s_or_b64 exec, exec, s[0:1]
	s_waitcnt vmcnt(63) expcnt(7) lgkmcnt(15)
	s_barrier
.LBB0_273:
	s_cmp_eq_u32 s101, -1
	s_cbranch_scc1 .Llc_stride
	s_add_i32 s101, s101, 1
	v_readlane_b32 s100, v255, 0
	s_nop 3
	s_cmp_lt_u32 s101, 3
	s_cbranch_scc0 .Llc_k3
	s_mul_i32 s22, s100, 171
	s_lshr_b32 s22, s22, 9
	s_mul_i32 s22, s22, 3
	s_sub_i32 s22, s100, s22
	s_add_i32 s22, s22, s101
	s_cmp_gt_u32 s22, 2
	s_cselect_b32 s0, 3, 0
	s_sub_i32 s22, s22, s0
	s_mul_i32 s22, s22, 0x108
	s_add_i32 s22, s22, s100
	s_branch .LBB0_274
